# NSA item loop: end-of-item workgroup barrier sunk below the next item's prologue load issue
# baseline (speedup 1.0000x reference)
.LBB0_786:
	s_lshl_b32 s0, s90, 3
	s_or_b32 s68, s0, s70
	s_mul_hi_u32 s0, s68, 0x55555556
	s_lshl_b32 s93, s2, 1
	s_mul_i32 s1, s0, 3
	s_add_i32 s93, s93, s53
	s_sub_i32 s1, s68, s1
	s_sub_i32 s92, 63, s93
	s_lshl_b32 s1, s1, 2
	s_or_b32 s33, s1, s72
	s_lshl_b32 s1, s92, 6
	s_or_b32 s91, s1, s73
	v_or_b32_e32 v210, s91, v172
	v_ashrrev_i32_e32 v211, 31, v210
	v_lshlrev_b64 v[0:1], 8, v[210:211]
	v_lshl_add_u64 v[48:49], v[192:193], 0, v[0:1]
	flat_load_dwordx4 v[24:27], v[190:191] offset:64
	flat_load_dwordx4 v[28:31], v[190:191] offset:80
	flat_load_dwordx4 v[8:11], v[190:191] offset:192
	flat_load_dwordx4 v[12:15], v[190:191] offset:208
	flat_load_dwordx4 v[4:7], v[48:49] offset:128
	flat_load_dwordx4 v[66:69], v[48:49] offset:144
	flat_load_dwordx4 v[0:3], v[48:49] offset:160
	flat_load_dwordx4 v[72:75], v[48:49] offset:176
	s_lshl_b32 s62, s0, 12
	v_lshl_add_u64 v[212:213], v[210:211], 0, s[62:63]
	v_mad_u64_u32 v[56:57], s[0:1], v212, s77, v[188:189]
	v_mad_i32_i24 v57, v213, s77, v57
	s_lshl_b32 s62, s33, 7
	v_lshl_add_u64 v[16:17], v[56:57], 0, s[62:63]
	v_lshl_add_u64 v[70:71], v[16:17], 0, v[168:169]
	global_load_dwordx4 v[76:79], v[70:71], off offset:32
	global_load_dwordx4 v[80:83], v[70:71], off offset:96
	global_load_dwordx4 v[84:87], v[70:71], off
	global_load_dwordx4 v[88:91], v[70:71], off offset:64
	flat_load_dwordx4 v[44:47], v[190:191]
	flat_load_dwordx4 v[40:43], v[190:191] offset:16
	flat_load_dwordx4 v[36:39], v[190:191] offset:128
	flat_load_dwordx4 v[32:35], v[190:191] offset:144
	flat_load_dwordx4 v[20:23], v[48:49]
	flat_load_dwordx4 v[52:55], v[48:49] offset:16
	flat_load_dwordx4 v[16:19], v[48:49] offset:32
	s_nop 0
	flat_load_dwordx4 v[48:51], v[48:49] offset:48
	s_barrier
	s_mul_i32 s62, s33, 3
	s_mov_b32 s69, s63
	s_waitcnt vmcnt(0) lgkmcnt(0)
	v_mov_b32_e32 v60, v24
	v_mov_b32_e32 v64, v28
	v_mov_b32_e32 v58, v8
	v_mov_b32_e32 v59, v10
	v_mov_b32_e32 v10, v9
	v_mov_b32_e32 v8, v3
	v_mov_b32_e32 v9, v75
	v_mov_b32_e32 v3, v74
	v_lshlrev_b32_e32 v75, 16, v85
	v_lshlrev_b32_e32 v74, 16, v84
	v_and_b32_e32 v85, 0xffff0000, v85
	v_and_b32_e32 v84, 0xffff0000, v84
	v_pk_mul_f32 v[112:113], v[74:75], v[74:75]
	v_pk_mul_f32 v[114:115], v[84:85], v[84:85]
	v_lshlrev_b32_e32 v93, 16, v81
	v_and_b32_e32 v81, 0xffff0000, v81
	v_add_f32_e32 v112, v112, v114
	v_mov_b32_e32 v62, v12
	v_mov_b32_e32 v63, v14
	v_mov_b32_e32 v14, v13
	v_mov_b32_e32 v12, v5
	v_mov_b32_e32 v13, v67
	v_mov_b32_e32 v5, v66
	v_mov_b32_e32 v66, v81
	v_mov_b32_e32 v67, v93
	v_lshlrev_b32_e32 v121, 16, v87
	v_lshlrev_b32_e32 v120, 16, v86
	v_add_f32_e32 v112, v113, v112
	v_pk_mul_f32 v[108:109], v[66:67], v[66:67]
	v_mov_b32_e32 v66, v44
	v_mov_b32_e32 v67, v46
	v_mov_b32_e32 v46, v45
	v_and_b32_e32 v87, 0xffff0000, v87
	v_and_b32_e32 v86, 0xffff0000, v86
	v_pk_mul_f32 v[44:45], v[120:121], v[120:121]
	v_add_f32_e32 v112, v115, v112
	v_pk_mul_f32 v[124:125], v[86:87], v[86:87]
	v_add_f32_e32 v44, v44, v112
	v_add_f32_e32 v44, v124, v44
	v_mov_b32_e32 v65, v30
	v_mov_b32_e32 v30, v29
	v_mov_b32_e32 v28, v1
	v_mov_b32_e32 v29, v73
	v_mov_b32_e32 v1, v72
	v_lshlrev_b32_e32 v73, 16, v77
	v_lshlrev_b32_e32 v72, 16, v76
	v_add_f32_e32 v44, v45, v44
	v_mov_b32_e32 v61, v26
	v_mov_b32_e32 v26, v25
	v_mov_b32_e32 v24, v7
	v_mov_b32_e32 v25, v69
	v_mov_b32_e32 v7, v68
	v_and_b32_e32 v77, 0xffff0000, v77
	v_and_b32_e32 v76, 0xffff0000, v76
	v_pk_mul_f32 v[68:69], v[72:73], v[72:73]
	v_add_f32_e32 v44, v125, v44
	v_pk_mul_f32 v[98:99], v[76:77], v[76:77]
	v_add_f32_e32 v44, v68, v44
	v_add_f32_e32 v44, v98, v44
	v_lshlrev_b32_e32 v95, 16, v79
	v_lshlrev_b32_e32 v94, 16, v78
	v_add_f32_e32 v44, v69, v44
	v_and_b32_e32 v79, 0xffff0000, v79
	v_and_b32_e32 v78, 0xffff0000, v78
	v_pk_mul_f32 v[100:101], v[94:95], v[94:95]
	v_add_f32_e32 v44, v99, v44
	v_pk_mul_f32 v[102:103], v[78:79], v[78:79]
	v_add_f32_e32 v44, v100, v44
	v_add_f32_e32 v44, v102, v44
	v_lshlrev_b32_e32 v111, 16, v89
	v_lshlrev_b32_e32 v110, 16, v88
	v_add_f32_e32 v44, v101, v44
	v_and_b32_e32 v89, 0xffff0000, v89
	v_and_b32_e32 v88, 0xffff0000, v88
	v_pk_mul_f32 v[116:117], v[110:111], v[110:111]
	v_add_f32_e32 v44, v103, v44
	v_pk_mul_f32 v[118:119], v[88:89], v[88:89]
	v_add_f32_e32 v44, v116, v44
	v_add_f32_e32 v44, v118, v44
	v_lshlrev_b32_e32 v123, 16, v91
	v_lshlrev_b32_e32 v122, 16, v90
	v_add_f32_e32 v44, v117, v44
	v_and_b32_e32 v91, 0xffff0000, v91
	v_and_b32_e32 v90, 0xffff0000, v90
	v_pk_mul_f32 v[126:127], v[122:123], v[122:123]
	v_add_f32_e32 v44, v119, v44
	v_pk_mul_f32 v[128:129], v[90:91], v[90:91]
	v_add_f32_e32 v44, v126, v44
	v_add_f32_e32 v44, v128, v44
	v_add_f32_e32 v44, v127, v44
	v_lshlrev_b32_e32 v92, 16, v80
	v_add_f32_e32 v44, v129, v44
	v_and_b32_e32 v80, 0xffff0000, v80
	v_fmac_f32_e32 v44, v92, v92
	v_lshlrev_b32_e32 v96, 16, v82
	v_and_b32_e32 v82, 0xffff0000, v82
	v_fmac_f32_e32 v44, v80, v80
	v_mov_b32_e32 v104, v82
	v_mov_b32_e32 v105, v96
	v_add_f32_e32 v44, v109, v44
	v_lshlrev_b32_e32 v97, 16, v83
	v_and_b32_e32 v83, 0xffff0000, v83
	v_pk_mul_f32 v[104:105], v[104:105], v[104:105]
	v_add_f32_e32 v44, v108, v44
	v_mov_b32_e32 v106, v83
	v_mov_b32_e32 v107, v97
	v_add_f32_e32 v44, v105, v44
	v_pk_mul_f32 v[106:107], v[106:107], v[106:107]
	v_add_f32_e32 v44, v104, v44
	v_add_f32_e32 v44, v107, v44
	v_add_f32_e32 v45, v106, v44
	ds_bpermute_b32 v98, v177, v45
	v_mov_b32_e32 v44, v21
	v_mov_b32_e32 v68, v36
	v_mov_b32_e32 v69, v38
	v_mov_b32_e32 v38, v37
	s_waitcnt lgkmcnt(0)
	v_add_f32_e32 v21, v45, v98
	v_fmamk_f32 v21, v21, 0x3c800000, v226
	v_mul_f32_e32 v36, 0x4f800000, v21
	v_cmp_gt_f32_e32 vcc, s79, v21
	v_mov_b32_e32 v45, v53
	s_nop 0
	v_cndmask_b32_e32 v36, v21, v36, vcc
	v_sqrt_f32_e32 v37, v36
	v_mov_b32_e32 v21, v52
	v_mov_b32_e32 v52, v23
	v_add_u32_e32 v23, -1, v37
	v_fma_f32 v53, -v23, v37, v36
	v_cmp_ge_f32_e64 s[0:1], 0, v53
	v_add_u32_e32 v53, 1, v37
	s_nop 0
	v_cndmask_b32_e64 v23, v37, v23, s[0:1]
	v_fma_f32 v37, -v53, v37, v36
	v_cmp_lt_f32_e64 s[0:1], 0, v37
	s_nop 1
	v_cndmask_b32_e64 v23, v23, v53, s[0:1]
	v_mul_f32_e32 v37, 0x37800000, v23
	v_cndmask_b32_e32 v23, v23, v37, vcc
	v_cmp_class_f32_e32 vcc, v36, v227
	v_mov_b32_e32 v53, v55
	v_mov_b32_e32 v37, 0
	v_cndmask_b32_e32 v36, v23, v36, vcc
	v_div_scale_f32 v98, s[0:1], v36, v36, s80
	v_rcp_f32_e32 v99, v98
	v_mov_b32_e32 v23, v54
	v_fma_f32 v54, -v98, v99, 1.0
	v_fmac_f32_e32 v99, v54, v99
	v_div_scale_f32 v54, vcc, s80, v36, s80
	v_mul_f32_e32 v55, v54, v99
	v_fma_f32 v100, -v98, v55, v54
	v_fmac_f32_e32 v55, v100, v99
	v_fma_f32 v54, -v98, v55, v54
	v_div_fmas_f32 v54, v54, v99, v55
	v_div_fixup_f32 v36, v54, v36, s80
	v_pk_mul_f32 v[54:55], v[66:67], v[36:37] op_sel_hi:[1,0]
	v_pk_mul_f32 v[100:101], v[46:47], v[36:37] op_sel_hi:[1,0]
	v_pk_mul_f32 v[74:75], v[54:55], v[74:75]
	v_mov_b32_e32 v55, v42
	v_mov_b32_e32 v42, v41
	v_mov_b32_e32 v54, v40
	v_pk_mul_f32 v[40:41], v[42:43], v[36:37] op_sel_hi:[1,0]
	v_pk_mul_f32 v[84:85], v[100:101], v[84:85]
	v_pk_mul_f32 v[86:87], v[40:41], v[86:87]
	v_pk_mul_f32 v[40:41], v[60:61], v[36:37] op_sel_hi:[1,0]
	v_pk_mul_f32 v[98:99], v[54:55], v[36:37] op_sel_hi:[1,0]
	v_pk_mul_f32 v[100:101], v[40:41], v[72:73]
	v_pk_mul_f32 v[40:41], v[64:65], v[36:37] op_sel_hi:[1,0]
	v_mov_b32_e32 v73, v34
	v_mov_b32_e32 v34, v33
	v_pk_mul_f32 v[94:95], v[40:41], v[94:95]
	v_pk_mul_f32 v[40:41], v[26:27], v[36:37] op_sel_hi:[1,0]
	v_mov_b32_e32 v72, v32
	v_pk_mul_f32 v[32:33], v[34:35], v[36:37] op_sel_hi:[1,0]
	v_pk_mul_f32 v[102:103], v[40:41], v[76:77]
	v_pk_mul_f32 v[40:41], v[30:31], v[36:37] op_sel_hi:[1,0]
	v_pk_mul_f32 v[90:91], v[32:33], v[90:91]
	v_pk_mul_f32 v[32:33], v[58:59], v[36:37] op_sel_hi:[1,0]
	v_pk_mul_f32 v[104:105], v[40:41], v[78:79]
	v_pk_mul_f32 v[40:41], v[68:69], v[36:37] op_sel_hi:[1,0]
	v_pk_mul_f32 v[92:93], v[32:33], v[92:93]
	v_pk_mul_f32 v[32:33], v[62:63], v[36:37] op_sel_hi:[1,0]
	v_pk_mul_f32 v[76:77], v[40:41], v[110:111]
	v_pk_mul_f32 v[40:41], v[72:73], v[36:37] op_sel_hi:[1,0]
	v_pk_mul_f32 v[106:107], v[32:33], v[96:97]
	v_pk_mul_f32 v[32:33], v[10:11], v[36:37] op_sel_hi:[1,0]
	v_pk_mul_f32 v[78:79], v[40:41], v[122:123]
	v_pk_mul_f32 v[40:41], v[38:39], v[36:37] op_sel_hi:[1,0]
	v_pk_mul_f32 v[108:109], v[32:33], v[80:81]
	v_pk_mul_f32 v[32:33], v[14:15], v[36:37] op_sel_hi:[1,0]
	v_pk_mul_f32 v[88:89], v[40:41], v[88:89]
	v_pk_mul_f32 v[110:111], v[32:33], v[82:83]
	v_pk_mul_f32 v[32:33], v[20:21], v[76:77]
	v_pk_mul_f32 v[80:81], v[6:7], v[108:109]
	v_pk_fma_f32 v[112:113], v[44:45], v[74:75], v[32:33]
	v_pk_mul_f32 v[32:33], v[22:23], v[88:89]
	v_pk_mul_f32 v[98:99], v[98:99], v[120:121]
	v_pk_fma_f32 v[114:115], v[52:53], v[84:85], v[32:33]
	v_mov_b32_e32 v32, v17
	v_mov_b32_e32 v17, v48
	v_mov_b32_e32 v33, v49
	v_pk_mul_f32 v[40:41], v[16:17], v[78:79]
	v_pk_fma_f32 v[118:119], v[24:25], v[102:103], v[80:81]
	v_pk_mul_f32 v[80:81], v[0:1], v[106:107]
	v_pk_mul_f32 v[76:77], v[44:45], v[76:77]
	v_pk_fma_f32 v[116:117], v[32:33], v[98:99], v[40:41]
	v_mov_b32_e32 v40, v19
	v_mov_b32_e32 v41, v51
	v_pk_fma_f32 v[120:121], v[28:29], v[94:95], v[80:81]
	v_pk_mul_f32 v[80:81], v[2:3], v[110:111]
	v_pk_fma_f32 v[74:75], v[20:21], v[74:75], v[76:77] neg_lo:[0,0,1] neg_hi:[0,0,1]
	v_pk_mul_f32 v[76:77], v[52:53], v[88:89]
	v_mov_b32_e32 v19, v50
	v_pk_fma_f32 v[122:123], v[8:9], v[104:105], v[80:81]
	v_pk_fma_f32 v[76:77], v[22:23], v[84:85], v[76:77] neg_lo:[0,0,1] neg_hi:[0,0,1]
	v_pk_mul_f32 v[80:81], v[40:41], v[90:91]
	v_pk_mul_f32 v[78:79], v[32:33], v[78:79]
	v_pk_fma_f32 v[80:81], v[18:19], v[86:87], v[80:81] neg_lo:[0,0,1] neg_hi:[0,0,1]
	v_bfe_u32 v84, v76, 16, 1
	v_pk_mul_f32 v[48:49], v[18:19], v[90:91]
	v_pk_fma_f32 v[78:79], v[16:17], v[98:99], v[78:79] neg_lo:[0,0,1] neg_hi:[0,0,1]
	v_bfe_u32 v36, v81, 16, 1
	v_bfe_u32 v82, v80, 16, 1
	v_bfe_u32 v83, v77, 16, 1
	v_add3_u32 v90, v76, v84, s81
	v_bfe_u32 v76, v74, 16, 1
	v_add3_u32 v91, v77, v83, s81
	v_add3_u32 v96, v80, v82, s81
	v_add3_u32 v36, v81, v36, s81
	v_bfe_u32 v77, v75, 16, 1
	v_bfe_u32 v80, v78, 16, 1
	v_bfe_u32 v81, v79, 16, 1
	v_add3_u32 v74, v74, v76, s81
	v_add3_u32 v97, v79, v81, s81
	v_add3_u32 v82, v78, v80, s81
	v_add3_u32 v83, v75, v77, s81
	v_lshrrev_b32_e32 v124, 16, v74
	global_load_dwordx4 v[74:77], v[70:71], off offset:128
	global_load_dwordx4 v[78:81], v[70:71], off offset:160
	v_pk_fma_f32 v[50:51], v[40:41], v[86:87], v[48:49]
	v_lshrrev_b32_e32 v125, 16, v83
	v_lshrrev_b32_e32 v98, 16, v82
	global_load_dwordx4 v[82:85], v[70:71], off offset:192
	global_load_dwordx4 v[86:89], v[70:71], off offset:224
	v_lshrrev_b32_e32 v70, 16, v97
	v_pk_mul_f32 v[48:49], v[4:5], v[92:93]
	v_and_or_b32 v99, v36, s78, v70
	v_and_or_b32 v98, v96, s78, v98
	v_and_or_b32 v97, v91, s78, v125
	v_and_or_b32 v96, v90, s78, v124
	v_pk_mul_f32 v[70:71], v[12:13], v[92:93]
	v_pk_mul_f32 v[90:91], v[24:25], v[108:109]
	v_pk_mul_f32 v[92:93], v[28:29], v[106:107]
	v_pk_fma_f32 v[90:91], v[6:7], v[102:103], v[90:91] neg_lo:[0,0,1] neg_hi:[0,0,1]
	v_pk_fma_f32 v[92:93], v[0:1], v[94:95], v[92:93] neg_lo:[0,0,1] neg_hi:[0,0,1]
	v_pk_mul_f32 v[94:95], v[8:9], v[110:111]
	v_bfe_u32 v102, v90, 16, 1
	v_pk_fma_f32 v[94:95], v[2:3], v[104:105], v[94:95] neg_lo:[0,0,1] neg_hi:[0,0,1]
	v_pk_fma_f32 v[48:49], v[12:13], v[100:101], v[48:49]
	v_pk_fma_f32 v[70:71], v[4:5], v[100:101], v[70:71] neg_lo:[0,0,1] neg_hi:[0,0,1]
	v_bfe_u32 v100, v94, 16, 1
	v_add3_u32 v90, v90, v102, s81
	v_bfe_u32 v102, v93, 16, 1
	v_bfe_u32 v36, v95, 16, 1
	v_add3_u32 v94, v94, v100, s81
	v_bfe_u32 v100, v71, 16, 1
	v_add3_u32 v93, v93, v102, s81
	v_bfe_u32 v101, v91, 16, 1
	v_add3_u32 v36, v95, v36, s81
	v_bfe_u32 v95, v70, 16, 1
	v_add3_u32 v71, v71, v100, s81
	v_lshrrev_b32_e32 v93, 16, v93
	v_add3_u32 v91, v91, v101, s81
	v_bfe_u32 v101, v92, 16, 1
	v_add3_u32 v70, v70, v95, s81
	v_lshrrev_b32_e32 v71, 16, v71
	v_and_or_b32 v103, v36, s78, v93
	v_bfe_u32 v36, v51, 16, 1
	v_add3_u32 v92, v92, v101, s81
	v_lshrrev_b32_e32 v70, 16, v70
	v_and_or_b32 v101, v91, s78, v71
	v_add3_u32 v36, v51, v36, s81
	v_bfe_u32 v51, v112, 16, 1
	v_bfe_u32 v91, v116, 16, 1
	v_and_or_b32 v100, v90, s78, v70
	v_bfe_u32 v70, v50, 16, 1
	v_bfe_u32 v90, v114, 16, 1
	v_add3_u32 v91, v116, v91, s81
	v_add3_u32 v51, v112, v51, s81
	v_add3_u32 v90, v114, v90, s81
	v_add3_u32 v50, v50, v70, s81
	v_lshrrev_b32_e32 v51, 16, v51
	v_lshrrev_b32_e32 v91, 16, v91
	v_and_or_b32 v106, v50, s78, v91
	v_and_or_b32 v104, v90, s78, v51
	v_bfe_u32 v50, v122, 16, 1
	v_bfe_u32 v51, v119, 16, 1
	v_add3_u32 v145, v119, v51, s81
	v_add3_u32 v146, v122, v50, s81
	v_bfe_u32 v50, v120, 16, 1
	v_bfe_u32 v51, v121, 16, 1
	v_add3_u32 v149, v121, v51, s81
	v_add3_u32 v150, v120, v50, s81
	v_bfe_u32 v70, v113, 16, 1
	v_lshrrev_b32_e32 v92, 16, v92
	v_bfe_u32 v71, v115, 16, 1
	v_add3_u32 v70, v113, v70, s81
	v_and_or_b32 v102, v94, s78, v92
	v_add3_u32 v71, v115, v71, s81
	v_bfe_u32 v92, v117, 16, 1
	v_lshrrev_b32_e32 v70, 16, v70
	v_add3_u32 v92, v117, v92, s81
	v_and_or_b32 v105, v71, s78, v70
	v_bfe_u32 v70, v118, 16, 1
	v_lshrrev_b32_e32 v92, 16, v92
	v_add3_u32 v144, v118, v70, s81
	v_and_or_b32 v107, v36, s78, v92
	v_bfe_u32 v36, v123, 16, 1
	s_waitcnt vmcnt(3)
	v_lshlrev_b32_e32 v121, 16, v75
	v_lshlrev_b32_e32 v120, 16, v74
	v_and_b32_e32 v75, 0xffff0000, v75
	v_and_b32_e32 v74, 0xffff0000, v74
	v_pk_mul_f32 v[124:125], v[120:121], v[120:121]
	v_pk_mul_f32 v[126:127], v[74:75], v[74:75]
	v_lshlrev_b32_e32 v133, 16, v77
	v_add_f32_e32 v124, v124, v126
	v_lshlrev_b32_e32 v132, 16, v76
	v_add_f32_e32 v124, v125, v124
	v_and_b32_e32 v77, 0xffff0000, v77
	v_and_b32_e32 v76, 0xffff0000, v76
	v_pk_mul_f32 v[136:137], v[132:133], v[132:133]
	v_add_f32_e32 v124, v127, v124
	v_pk_mul_f32 v[138:139], v[76:77], v[76:77]
	v_add_f32_e32 v124, v136, v124
	v_add_f32_e32 v124, v138, v124
	s_waitcnt vmcnt(2)
	v_lshlrev_b32_e32 v51, 16, v79
	v_lshlrev_b32_e32 v50, 16, v78
	v_add_f32_e32 v124, v137, v124
	v_and_b32_e32 v71, 0xffff0000, v79
	v_and_b32_e32 v70, 0xffff0000, v78
	v_pk_mul_f32 v[90:91], v[50:51], v[50:51]
	v_add_f32_e32 v124, v139, v124
	v_pk_mul_f32 v[92:93], v[70:71], v[70:71]
	v_add_f32_e32 v90, v90, v124
	v_add_f32_e32 v90, v92, v90
	v_lshlrev_b32_e32 v113, 16, v81
	v_lshlrev_b32_e32 v112, 16, v80
	v_add_f32_e32 v90, v91, v90
	v_and_b32_e32 v81, 0xffff0000, v81
	v_and_b32_e32 v80, 0xffff0000, v80
	v_pk_mul_f32 v[108:109], v[112:113], v[112:113]
	v_add_f32_e32 v90, v93, v90
	v_pk_mul_f32 v[110:111], v[80:81], v[80:81]
	v_add_f32_e32 v90, v108, v90
	v_add_f32_e32 v90, v110, v90
	v_add3_u32 v36, v123, v36, s81
	s_waitcnt vmcnt(1)
	v_lshlrev_b32_e32 v123, 16, v83
	v_lshlrev_b32_e32 v122, 16, v82
	v_add_f32_e32 v90, v109, v90
	v_and_b32_e32 v83, 0xffff0000, v83
	v_and_b32_e32 v82, 0xffff0000, v82
	v_pk_mul_f32 v[128:129], v[122:123], v[122:123]
	v_add_f32_e32 v90, v111, v90
	v_pk_mul_f32 v[130:131], v[82:83], v[82:83]
	v_add_f32_e32 v90, v128, v90
	v_add_f32_e32 v90, v130, v90
	v_lshlrev_b32_e32 v135, 16, v85
	v_lshlrev_b32_e32 v134, 16, v84
	v_add_f32_e32 v90, v129, v90
	v_and_b32_e32 v85, 0xffff0000, v85
	v_and_b32_e32 v84, 0xffff0000, v84
	v_pk_mul_f32 v[140:141], v[134:135], v[134:135]
	v_add_f32_e32 v90, v131, v90
	v_pk_mul_f32 v[142:143], v[84:85], v[84:85]
	v_add_f32_e32 v90, v140, v90
	v_add_f32_e32 v90, v142, v90
	v_add_f32_e32 v90, v141, v90
	s_waitcnt vmcnt(0)
	v_lshlrev_b32_e32 v79, 16, v87
	v_lshlrev_b32_e32 v78, 16, v86
	v_and_b32_e32 v87, 0xffff0000, v87
	v_add_f32_e32 v90, v143, v90
	v_and_b32_e32 v86, 0xffff0000, v86
	v_mov_b32_e32 v94, v87
	v_mov_b32_e32 v95, v79
	v_fmac_f32_e32 v90, v78, v78
	v_pk_mul_f32 v[94:95], v[94:95], v[94:95]
	v_lshlrev_b32_e32 v114, 16, v88
	v_and_b32_e32 v88, 0xffff0000, v88
	v_fmac_f32_e32 v90, v86, v86
	v_mov_b32_e32 v116, v88
	v_mov_b32_e32 v117, v114
	v_add_f32_e32 v90, v95, v90
	v_lshlrev_b32_e32 v115, 16, v89
	v_and_b32_e32 v89, 0xffff0000, v89
	v_pk_mul_f32 v[116:117], v[116:117], v[116:117]
	v_add_f32_e32 v90, v94, v90
	v_mov_b32_e32 v118, v89
	v_mov_b32_e32 v119, v115
	v_add_f32_e32 v90, v117, v90
	v_pk_mul_f32 v[118:119], v[118:119], v[118:119]
	v_add_f32_e32 v90, v116, v90
	v_add_f32_e32 v90, v119, v90
	v_add_f32_e32 v90, v118, v90
	ds_bpermute_b32 v91, v177, v90
	v_lshrrev_b32_e32 v93, 16, v149
	v_and_or_b32 v111, v36, s78, v93
	v_bfe_u32 v147, v48, 16, 1
	v_add3_u32 v48, v48, v147, s81
	s_waitcnt lgkmcnt(0)
	v_add_f32_e32 v90, v90, v91
	v_fmamk_f32 v90, v90, 0x3c800000, v226
	v_mul_f32_e32 v91, 0x4f800000, v90
	v_cmp_gt_f32_e32 vcc, s79, v90
	v_bfe_u32 v148, v49, 16, 1
	v_lshrrev_b32_e32 v48, 16, v48
	v_cndmask_b32_e32 v90, v90, v91, vcc
	v_sqrt_f32_e32 v91, v90
	v_add3_u32 v49, v49, v148, s81
	v_and_or_b32 v108, v144, s78, v48
	v_lshrrev_b32_e32 v49, 16, v49
	v_add_u32_e32 v36, -1, v91
	v_fma_f32 v93, -v36, v91, v90
	v_cmp_ge_f32_e64 s[0:1], 0, v93
	v_add_u32_e32 v93, 1, v91
	v_lshrrev_b32_e32 v92, 16, v150
	v_cndmask_b32_e64 v36, v91, v36, s[0:1]
	v_fma_f32 v91, -v93, v91, v90
	v_cmp_lt_f32_e64 s[0:1], 0, v91
	v_and_or_b32 v109, v145, s78, v49
	v_and_or_b32 v110, v146, s78, v92
	v_cndmask_b32_e64 v36, v36, v93, s[0:1]
	v_mul_f32_e32 v91, 0x37800000, v36
	v_cndmask_b32_e32 v36, v36, v91, vcc
	v_cmp_class_f32_e32 vcc, v90, v227
	s_nop 1
	v_cndmask_b32_e32 v36, v36, v90, vcc
	v_div_scale_f32 v90, s[0:1], v36, v36, s80
	v_rcp_f32_e32 v91, v90
	s_lshl_b64 s[0:1], s[68:69], 15
	v_lshl_add_u64 v[214:215], v[196:197], 0, s[0:1]
	s_ashr_i32 s0, s91, 4
	v_fma_f32 v48, -v90, v91, 1.0
	v_fmac_f32_e32 v91, v48, v91
	v_div_scale_f32 v48, vcc, s80, v36, s80
	v_mul_f32_e32 v49, v48, v91
	v_fma_f32 v92, -v90, v49, v48
	v_fmac_f32_e32 v49, v92, v91
	v_fma_f32 v48, -v90, v49, v48
	v_div_fmas_f32 v48, v48, v91, v49
	v_div_fixup_f32 v36, v48, v36, s80
	v_pk_mul_f32 v[10:11], v[10:11], v[36:37] op_sel_hi:[1,0]
	v_pk_mul_f32 v[60:61], v[60:61], v[36:37] op_sel_hi:[1,0]
	v_pk_mul_f32 v[26:27], v[26:27], v[36:37] op_sel_hi:[1,0]
	v_pk_mul_f32 v[58:59], v[58:59], v[36:37] op_sel_hi:[1,0]
	v_pk_mul_f32 v[62:63], v[62:63], v[36:37] op_sel_hi:[1,0]
	v_pk_mul_f32 v[10:11], v[10:11], v[86:87]
	v_pk_mul_f32 v[50:51], v[60:61], v[50:51]
	v_pk_mul_f32 v[60:61], v[64:65], v[36:37] op_sel_hi:[1,0]
	v_pk_mul_f32 v[26:27], v[26:27], v[70:71]
	v_pk_mul_f32 v[58:59], v[58:59], v[78:79]
	v_pk_mul_f32 v[62:63], v[62:63], v[114:115]
	v_pk_mul_f32 v[78:79], v[6:7], v[10:11]
	v_pk_mul_f32 v[10:11], v[24:25], v[10:11]
	v_pk_mul_f32 v[60:61], v[60:61], v[112:113]
	v_pk_mul_f32 v[30:31], v[30:31], v[36:37] op_sel_hi:[1,0]
	v_pk_fma_f32 v[6:7], v[6:7], v[26:27], v[10:11] neg_lo:[0,0,1] neg_hi:[0,0,1]
	v_pk_mul_f32 v[10:11], v[28:29], v[62:63]
	v_pk_mul_f32 v[48:49], v[66:67], v[36:37] op_sel_hi:[1,0]
	v_pk_mul_f32 v[30:31], v[30:31], v[80:81]
	v_pk_mul_f32 v[64:65], v[68:69], v[36:37] op_sel_hi:[1,0]
	v_pk_mul_f32 v[66:67], v[72:73], v[36:37] op_sel_hi:[1,0]
	v_pk_mul_f32 v[80:81], v[0:1], v[62:63]
	v_pk_fma_f32 v[0:1], v[0:1], v[60:61], v[10:11] neg_lo:[0,0,1] neg_hi:[0,0,1]
	v_lshl_add_u64 v[10:11], s[62:63], 1, v[56:57]
	v_pk_mul_f32 v[54:55], v[54:55], v[36:37] op_sel_hi:[1,0]
	v_pk_mul_f32 v[64:65], v[64:65], v[122:123]
	v_pk_mul_f32 v[66:67], v[66:67], v[134:135]
	v_add_co_u32_e32 v10, vcc, s82, v10
	v_pk_mul_f32 v[48:49], v[48:49], v[120:121]
	v_pk_mul_f32 v[54:55], v[54:55], v[132:133]
	v_pk_mul_f32 v[68:69], v[20:21], v[64:65]
	v_pk_mul_f32 v[72:73], v[16:17], v[66:67]
	v_addc_co_u32_e32 v11, vcc, 0, v11, vcc
	v_pk_fma_f32 v[68:69], v[44:45], v[48:49], v[68:69]
	v_pk_fma_f32 v[72:73], v[32:33], v[54:55], v[72:73]
	v_pk_mul_f32 v[44:45], v[44:45], v[64:65]
	v_pk_mul_f32 v[32:33], v[32:33], v[66:67]
	flat_load_dwordx3 v[164:166], v[10:11] offset:256
	global_load_dwordx4 v[64:67], v[214:215], off
	global_load_dwordx4 v[136:139], v[214:215], off offset:1024
	global_load_dwordx4 v[132:135], v[214:215], off offset:2048
	global_load_dwordx4 v[128:131], v[214:215], off offset:3072
	v_pk_mul_f32 v[14:15], v[14:15], v[36:37] op_sel_hi:[1,0]
	v_pk_mul_f32 v[38:39], v[38:39], v[36:37] op_sel_hi:[1,0]
	v_pk_mul_f32 v[14:15], v[14:15], v[88:89]
	v_pk_mul_f32 v[42:43], v[42:43], v[36:37] op_sel_hi:[1,0]
	v_pk_mul_f32 v[38:39], v[38:39], v[82:83]
	v_pk_mul_f32 v[82:83], v[2:3], v[14:15]
	v_pk_mul_f32 v[42:43], v[42:43], v[76:77]
	v_pk_mul_f32 v[76:77], v[4:5], v[58:59]
	v_pk_fma_f32 v[82:83], v[8:9], v[30:31], v[82:83]
	v_pk_mul_f32 v[8:9], v[8:9], v[14:15]
	v_pk_fma_f32 v[76:77], v[12:13], v[50:51], v[76:77]
	v_pk_mul_f32 v[12:13], v[12:13], v[58:59]
	v_pk_fma_f32 v[2:3], v[2:3], v[30:31], v[8:9] neg_lo:[0,0,1] neg_hi:[0,0,1]
	v_pk_fma_f32 v[4:5], v[4:5], v[50:51], v[12:13] neg_lo:[0,0,1] neg_hi:[0,0,1]
	v_bfe_u32 v8, v3, 16, 1
	v_bfe_u32 v9, v2, 16, 1
	v_pk_mul_f32 v[34:35], v[34:35], v[36:37] op_sel_hi:[1,0]
	v_bfe_u32 v10, v7, 16, 1
	v_bfe_u32 v11, v6, 16, 1
	v_add3_u32 v2, v2, v9, s81
	v_add3_u32 v3, v3, v8, s81
	v_bfe_u32 v8, v4, 16, 1
	v_bfe_u32 v9, v5, 16, 1
	v_pk_mul_f32 v[46:47], v[46:47], v[36:37] op_sel_hi:[1,0]
	v_pk_mul_f32 v[34:35], v[34:35], v[84:85]
	v_add3_u32 v6, v6, v11, s81
	v_add3_u32 v7, v7, v10, s81
	v_bfe_u32 v10, v0, 16, 1
	v_bfe_u32 v11, v1, 16, 1
	v_add3_u32 v5, v5, v9, s81
	v_add3_u32 v4, v4, v8, s81
	v_pk_mul_f32 v[46:47], v[46:47], v[74:75]
	v_pk_mul_f32 v[70:71], v[22:23], v[38:39]
	v_pk_mul_f32 v[74:75], v[18:19], v[34:35]
	v_add3_u32 v1, v1, v11, s81
	v_add3_u32 v0, v0, v10, s81
	v_lshrrev_b32_e32 v4, 16, v4
	v_lshrrev_b32_e32 v5, 16, v5
	v_pk_fma_f32 v[70:71], v[52:53], v[46:47], v[70:71]
	v_pk_fma_f32 v[74:75], v[40:41], v[42:43], v[74:75]
	v_pk_mul_f32 v[38:39], v[52:53], v[38:39]
	v_pk_fma_f32 v[16:17], v[16:17], v[54:55], v[32:33] neg_lo:[0,0,1] neg_hi:[0,0,1]
	v_pk_mul_f32 v[32:33], v[40:41], v[34:35]
	v_lshrrev_b32_e32 v0, 16, v0
	v_lshrrev_b32_e32 v1, 16, v1
	v_and_or_b32 v117, v7, s78, v5
	v_and_or_b32 v116, v6, s78, v4
	v_bfe_u32 v4, v68, 16, 1
	v_bfe_u32 v5, v69, 16, 1
	v_bfe_u32 v6, v72, 16, 1
	v_bfe_u32 v7, v73, 16, 1
	v_pk_fma_f32 v[22:23], v[22:23], v[46:47], v[38:39] neg_lo:[0,0,1] neg_hi:[0,0,1]
	v_pk_fma_f32 v[18:19], v[18:19], v[42:43], v[32:33] neg_lo:[0,0,1] neg_hi:[0,0,1]
	v_and_or_b32 v119, v3, s78, v1
	v_and_or_b32 v118, v2, s78, v0
	v_bfe_u32 v0, v75, 16, 1
	v_bfe_u32 v1, v74, 16, 1
	v_bfe_u32 v2, v71, 16, 1
	v_bfe_u32 v3, v70, 16, 1
	v_add3_u32 v7, v73, v7, s81
	v_add3_u32 v6, v72, v6, s81
	v_add3_u32 v5, v69, v5, s81
	v_add3_u32 v4, v68, v4, s81
	v_pk_fma_f32 v[80:81], v[28:29], v[60:61], v[80:81]
	v_pk_fma_f32 v[20:21], v[20:21], v[48:49], v[44:45] neg_lo:[0,0,1] neg_hi:[0,0,1]
	v_bfe_u32 v32, v19, 16, 1
	v_bfe_u32 v33, v18, 16, 1
	v_bfe_u32 v34, v23, 16, 1
	v_bfe_u32 v35, v22, 16, 1
	v_add3_u32 v3, v70, v3, s81
	v_add3_u32 v2, v71, v2, s81
	v_add3_u32 v1, v74, v1, s81
	v_add3_u32 v0, v75, v0, s81
	v_lshrrev_b32_e32 v4, 16, v4
	v_lshrrev_b32_e32 v5, 16, v5
	v_lshrrev_b32_e32 v6, 16, v6
	v_lshrrev_b32_e32 v7, 16, v7
	v_pk_fma_f32 v[78:79], v[24:25], v[26:27], v[78:79]
	v_add3_u32 v22, v22, v35, s81
	v_add3_u32 v23, v23, v34, s81
	v_add3_u32 v18, v18, v33, s81
	v_add3_u32 v19, v19, v32, s81
	v_bfe_u32 v32, v20, 16, 1
	v_bfe_u32 v33, v21, 16, 1
	v_bfe_u32 v34, v16, 16, 1
	v_bfe_u32 v35, v17, 16, 1
	v_and_or_b32 v123, v0, s78, v7
	v_and_or_b32 v122, v1, s78, v6
	v_and_or_b32 v121, v2, s78, v5
	v_and_or_b32 v120, v3, s78, v4
	v_bfe_u32 v4, v76, 16, 1
	v_bfe_u32 v5, v77, 16, 1
	v_bfe_u32 v6, v80, 16, 1
	v_bfe_u32 v7, v81, 16, 1
	s_min_i32 s0, s0, 0xfe
	v_add3_u32 v17, v17, v35, s81
	v_add3_u32 v16, v16, v34, s81
	v_add3_u32 v21, v21, v33, s81
	v_add3_u32 v20, v20, v32, s81
	v_bfe_u32 v0, v83, 16, 1
	v_bfe_u32 v1, v82, 16, 1
	v_bfe_u32 v2, v79, 16, 1
	v_bfe_u32 v3, v78, 16, 1
	v_add3_u32 v7, v81, v7, s81
	v_add3_u32 v6, v80, v6, s81
	v_add3_u32 v5, v77, v5, s81
	v_add3_u32 v4, v76, v4, s81
	s_add_i32 s0, s0, 32
	v_lshrrev_b32_e32 v20, 16, v20
	v_lshrrev_b32_e32 v21, 16, v21
	v_lshrrev_b32_e32 v16, 16, v16
	v_lshrrev_b32_e32 v17, 16, v17
	v_add3_u32 v3, v78, v3, s81
	v_add3_u32 v2, v79, v2, s81
	v_add3_u32 v1, v82, v1, s81
	v_add3_u32 v0, v83, v0, s81
	v_lshrrev_b32_e32 v4, 16, v4
	v_lshrrev_b32_e32 v5, 16, v5
	v_lshrrev_b32_e32 v6, 16, v6
	v_lshrrev_b32_e32 v7, 16, v7
	s_ashr_i32 s94, s0, 5
	v_and_or_b32 v115, v19, s78, v17
	v_and_or_b32 v114, v18, s78, v16
	v_and_or_b32 v113, v23, s78, v21
	v_and_or_b32 v112, v22, s78, v20
	v_and_or_b32 v127, v0, s78, v7
	v_and_or_b32 v126, v1, s78, v6
	v_and_or_b32 v125, v2, s78, v5
	s_cmp_lt_i32 s94, 1
	v_and_or_b32 v124, v3, s78, v4
	s_cbranch_scc1 .LBB0_789
	v_mov_b32_e32 v36, 0
	s_mov_b32 s2, 0
	v_mov_b32_e32 v209, 0xf149f2ca
	s_movk_i32 s3, 0x800
	v_mov_b32_e32 v32, v171
	v_mov_b32_e32 v211, 0xf149f2ca
	v_mov_b32_e32 v37, v36
